# gmlp: gelu(v) rows fetched one channel group ahead (shared wait with the gelu(u) loads)
# baseline (speedup 1.0000x reference)
; __device__ __forceinline__ bf16_t f2bf(float f) { return (bf16_t)(pkbf(f, 0.f) & 0xffffu); }
; __device__ __forceinline__ void gmlp_unit(const TI ti, CArgs& a, int l, int u, unsigned char* ldsg) {
;     ...
;     const float* gvg = a.in[9] + l * 1024; const float* wsp = a.in[10] + (size_t)l * 8 * 128 * 128; const float* bsp = a.in[11] + l * 8 * 128;
;     const int tt = w & 3, chh = w >> 2;
;     for (int g = 0; g < 8; ++g) {
;         {
;             const int s = tid & 127, cc = tid >> 7; const float rs = rstd[s]; const bf16_t* p = GV + (R0 + s) * 1024 + g * 128 + cc * 32;
; #pragma unroll
;             for (int q = 0; q < 4; ++q) {
;                 f32x4 x0, x1; unpack8(*(const u32x4*)(p + 8 * q), x0, x1);
;                 const float* gp = gvg + g * 128 + cc * 32 + 8 * q; const int c0 = cc * 32 + 8 * q;
;                 VNT[(c0 + 0) * 136 + s] = f2bf(x0.x * rs * gp[0]); VNT[(c0 + 1) * 136 + s] = f2bf(x0.y * rs * gp[1]);
;                 VNT[(c0 + 2) * 136 + s] = f2bf(x0.z * rs * gp[2]); VNT[(c0 + 3) * 136 + s] = f2bf(x0.w * rs * gp[3]);
;                 VNT[(c0 + 4) * 136 + s] = f2bf(x1.x * rs * gp[4]); VNT[(c0 + 5) * 136 + s] = f2bf(x1.y * rs * gp[5]);
;                 VNT[(c0 + 6) * 136 + s] = f2bf(x1.z * rs * gp[6]); VNT[(c0 + 7) * 136 + s] = f2bf(x1.w * rs * gp[7]);
;             }
;         }
;         __syncthreads();
.LBB0_446:
	s_mov_b64 s[46:47], 0
	v_mov_b64_e32 v[128:129], v[126:127]
	v_mov_b64_e32 v[130:131], v[124:125]
	v_mov_b64_e32 v[132:133], v[122:123]
	v_mov_b64_e32 v[134:135], v[120:121]
	v_mov_b64_e32 v[136:137], v[118:119]
	v_mov_b64_e32 v[138:139], v[116:117]
	v_mov_b64_e32 v[140:141], v[114:115]
	v_mov_b64_e32 v[142:143], v[112:113]
	v_mov_b64_e32 v[144:145], v[108:109]
	v_mov_b64_e32 v[146:147], v[106:107]
	v_lshl_add_u64 v[14:15], v[146:147], 0, s[42:43]
	global_load_dwordx4 v[222:225], v[14:15], off offset:16
	global_load_dwordx4 v[226:229], v[14:15], off
	global_load_dwordx4 v[230:233], v[14:15], off offset:-16
	global_load_dwordx4 v[234:237], v[14:15], off offset:-32
	s_waitcnt lgkmcnt(0)
	s_barrier
.LBB0_447:
	global_load_dwordx4 v[90:93], v[144:145], off offset:-256
	global_load_dwordx4 v[94:97], v[144:145], off offset:-240
	global_load_dwordx4 v[98:101], v[144:145], off offset:-192
	global_load_dwordx4 v[162:165], v[144:145], off offset:-176
	global_load_dwordx4 v[198:201], v[144:145], off offset:-128
	global_load_dwordx4 v[202:205], v[144:145], off offset:-112
	global_load_dwordx4 v[206:209], v[144:145], off offset:-64
	global_load_dwordx4 v[210:213], v[144:145], off offset:-48
	v_lshl_add_u64 v[14:15], v[146:147], 0, s[42:43]
	ds_read_b32 v0, v156
	v_lshl_add_u64 v[30:31], v[102:103], 0, s[46:47]
	v_lshl_add_u64 v[150:151], v[130:131], 0, s[42:43]
	v_lshl_add_u64 v[154:155], v[134:135], 0, s[42:43]
	v_lshl_add_u64 v[168:169], v[138:139], 0, s[42:43]
	s_mov_b32 s3, 0x5e01000
	s_mov_b64 s[4:5], 0x10000
	v_lshl_add_u64 v[146:147], v[146:147], 0, s[24:25]
	v_lshl_add_u64 v[138:139], v[138:139], 0, s[24:25]
	v_lshl_add_u64 v[134:135], v[134:135], 0, s[24:25]
	v_lshl_add_u64 v[130:131], v[130:131], 0, s[24:25]
	s_waitcnt vmcnt(8)
	v_mov_b32_e32 v2, v222
	v_mov_b32_e32 v3, v223
	v_mov_b32_e32 v4, v224
	v_mov_b32_e32 v5, v225
	v_mov_b32_e32 v6, v226
	v_mov_b32_e32 v7, v227
	v_mov_b32_e32 v8, v228
	v_mov_b32_e32 v9, v229
	v_mov_b32_e32 v10, v230
	v_mov_b32_e32 v11, v231
	v_mov_b32_e32 v12, v232
	v_mov_b32_e32 v13, v233
	v_mov_b32_e32 v14, v234
	v_mov_b32_e32 v15, v235
	v_mov_b32_e32 v16, v236
	v_mov_b32_e32 v17, v237
	v_lshlrev_b32_e32 v18, 16, v14
	v_and_b32_e32 v32, 0xffff0000, v14
	v_lshlrev_b32_e32 v33, 16, v15
	v_and_b32_e32 v34, 0xffff0000, v15
	v_lshlrev_b32_e32 v35, 16, v16
	v_and_b32_e32 v36, 0xffff0000, v16
	v_lshlrev_b32_e32 v37, 16, v17
	v_and_b32_e32 v38, 0xffff0000, v17
	s_waitcnt lgkmcnt(0)
	v_mul_f32_e32 v39, v0, v18
	global_load_dwordx4 v[14:17], v[30:31], off offset:48
	global_load_dwordx4 v[18:21], v[30:31], off offset:32
	global_load_dwordx4 v[22:25], v[30:31], off offset:16
	global_load_dwordx4 v[26:29], v[30:31], off
	s_waitcnt vmcnt(0)
	v_mul_f32_e32 v26, v26, v39
	v_cvt_pk_bf16_f32 v26, v26, s0
	ds_write_b16 v158, v26 offset:512
	v_mul_f32_e32 v26, v0, v32
	v_mul_f32_e32 v26, v27, v26
	v_cvt_pk_bf16_f32 v26, v26, s0
	ds_write_b16 v159, v26 offset:784
	v_mul_f32_e32 v26, v0, v33
	v_mul_f32_e32 v26, v26, v28
	v_cvt_pk_bf16_f32 v26, v26, s0
	ds_write_b16 v159, v26 offset:1056
	v_mul_f32_e32 v26, v0, v34
	v_mul_f32_e32 v26, v26, v29
	v_cvt_pk_bf16_f32 v26, v26, s0
	ds_write_b16 v159, v26 offset:1328
	v_mul_f32_e32 v26, v0, v35
	v_mul_f32_e32 v22, v26, v22
	v_cvt_pk_bf16_f32 v22, v22, s0
	ds_write_b16 v159, v22 offset:1600
	v_mul_f32_e32 v22, v0, v36
	v_mul_f32_e32 v22, v22, v23
	v_cvt_pk_bf16_f32 v22, v22, s0
	ds_write_b16 v159, v22 offset:1872
	v_mul_f32_e32 v22, v0, v37
	v_mul_f32_e32 v22, v22, v24
	v_cvt_pk_bf16_f32 v22, v22, s0
	ds_write_b16 v159, v22 offset:2144
	v_mul_f32_e32 v22, v0, v38
	v_mul_f32_e32 v22, v22, v25
	v_cvt_pk_bf16_f32 v22, v22, s0
	ds_write_b16 v159, v22 offset:2416
	v_lshlrev_b32_e32 v22, 16, v10
	v_and_b32_e32 v10, 0xffff0000, v10
	v_mul_f32_e32 v22, v0, v22
	v_mul_f32_e32 v10, v0, v10
	v_mul_f32_e32 v18, v18, v22
	v_mul_f32_e32 v10, v19, v10
	v_lshlrev_b32_e32 v23, 16, v11
	v_cvt_pk_bf16_f32 v18, v18, s0
	v_cvt_pk_bf16_f32 v10, v10, s0
	ds_write_b16 v158, v18 offset:2688
	ds_write_b16 v159, v10 offset:2960
	v_mul_f32_e32 v10, v0, v23
	v_mul_f32_e32 v10, v10, v20
	v_and_b32_e32 v11, 0xffff0000, v11
	v_cvt_pk_bf16_f32 v10, v10, s0
	ds_write_b16 v159, v10 offset:3232
	v_mul_f32_e32 v10, v0, v11
	v_mul_f32_e32 v10, v10, v21
	v_lshlrev_b32_e32 v24, 16, v12
	v_cvt_pk_bf16_f32 v10, v10, s0
	ds_write_b16 v159, v10 offset:3504
	v_mul_f32_e32 v10, v0, v24
	v_mul_f32_e32 v10, v10, v14
	v_and_b32_e32 v12, 0xffff0000, v12
	v_cvt_pk_bf16_f32 v10, v10, s0
	ds_write_b16 v159, v10 offset:3776
	v_mul_f32_e32 v10, v0, v12
	v_mul_f32_e32 v10, v10, v15
	v_lshlrev_b32_e32 v25, 16, v13
	v_cvt_pk_bf16_f32 v10, v10, s0
	ds_write_b16 v159, v10 offset:4048
	v_mul_f32_e32 v10, v0, v25
	v_mul_f32_e32 v10, v10, v16
	v_and_b32_e32 v13, 0xffff0000, v13
	v_cvt_pk_bf16_f32 v10, v10, s0
	ds_write_b16 v159, v10 offset:4320
	v_mul_f32_e32 v10, v0, v13
	v_mul_f32_e32 v10, v10, v17
	v_cvt_pk_bf16_f32 v10, v10, s0
	ds_write_b16 v159, v10 offset:4592
	v_lshlrev_b32_e32 v10, 16, v6
	v_and_b32_e32 v22, 0xffff0000, v6
	v_lshlrev_b32_e32 v23, 16, v7
	v_and_b32_e32 v24, 0xffff0000, v7
	v_lshlrev_b32_e32 v25, 16, v8
	v_and_b32_e32 v26, 0xffff0000, v8
	v_lshlrev_b32_e32 v27, 16, v9
	v_and_b32_e32 v28, 0xffff0000, v9
	v_mul_f32_e32 v29, v0, v10
	global_load_dwordx4 v[6:9], v[30:31], off offset:112
	global_load_dwordx4 v[10:13], v[30:31], off offset:96
	global_load_dwordx4 v[14:17], v[30:31], off offset:80
	global_load_dwordx4 v[18:21], v[30:31], off offset:64
	s_waitcnt vmcnt(0)
; #define MFMA32(a, b, c) __builtin_amdgcn_mfma_f32_32x32x16_bf16((a), (b), (c), 0, 0, 0)
; __device__ __forceinline__ bf16_t f2bf(float f) { return (bf16_t)(pkbf(f, 0.f) & 0xffffu); }
; __device__ __forceinline__ u32x4 pack8(f32x4 v0, f32x4 v1) { u32x4 o; o.x = pkbf(v0.x, v0.y); o.y = pkbf(v0.z, v0.w); o.z = pkbf(v1.x, v1.y); o.w = pkbf(v1.z, v1.w); return o; }
; __device__ __forceinline__ void gmlp_unit(const TI ti, CArgs& a, int l, int u, unsigned char* ldsg) {
;     ...
;             for (int q = 0; q < 4; ++q) {
;                 f32x4 x0, x1; unpack8(*(const u32x4*)(p + 8 * q), x0, x1);
;                 const float* gp = gvg + g * 128 + cc * 32 + 8 * q; const int c0 = cc * 32 + 8 * q;
;                 VNT[(c0 + 0) * 136 + s] = f2bf(x0.x * rs * gp[0]); VNT[(c0 + 1) * 136 + s] = f2bf(x0.y * rs * gp[1]);
;                 VNT[(c0 + 2) * 136 + s] = f2bf(x0.z * rs * gp[2]); VNT[(c0 + 3) * 136 + s] = f2bf(x0.w * rs * gp[3]);
;                 VNT[(c0 + 4) * 136 + s] = f2bf(x1.x * rs * gp[4]); VNT[(c0 + 5) * 136 + s] = f2bf(x1.y * rs * gp[5]);
;                 VNT[(c0 + 6) * 136 + s] = f2bf(x1.z * rs * gp[6]); VNT[(c0 + 7) * 136 + s] = f2bf(x1.w * rs * gp[7]);
;             }
;         }
;         __syncthreads();
;         f32x16 acc0, acc1;
; #pragma unroll
;         for (int i = 0; i < 16; ++i) { acc0[i] = 0.f; acc1[i] = 0.f; }
;         const float* wrow = wsp + ((size_t)g * 128 + tt * 32 + r) * 128;
; #pragma unroll
;         for (int ks = 0; ks < 8; ++ks) {
;             const f32x4 a0 = *(const f32x4*)(wrow + 16 * ks + 8 * h), a1 = *(const f32x4*)(wrow + 16 * ks + 8 * h + 4);
;             const bf16x8 af = __builtin_bit_cast(bf16x8, pack8(a0, a1));
;             const bf16x8 b0 = *(const bf16x8*)(VNT + (chh * 64 + r) * 136 + 16 * ks + 8 * h);
;             const bf16x8 b1 = *(const bf16x8*)(VNT + (chh * 64 + 32 + r) * 136 + 16 * ks + 8 * h);
;             acc0 = MFMA32(af, b0, acc0); acc1 = MFMA32(af, b1, acc1);
	v_mul_f32_e32 v18, v18, v29
	v_cvt_pk_bf16_f32 v18, v18, s0
	ds_write_b16 v158, v18 offset:4864
	v_mul_f32_e32 v18, v0, v22
	v_mul_f32_e32 v18, v19, v18
	v_cvt_pk_bf16_f32 v18, v18, s0
	ds_write_b16 v159, v18 offset:5136
	v_mul_f32_e32 v18, v0, v23
	v_mul_f32_e32 v18, v18, v20
	v_cvt_pk_bf16_f32 v18, v18, s0
	ds_write_b16 v159, v18 offset:5408
	v_mul_f32_e32 v18, v0, v24
	v_mul_f32_e32 v18, v18, v21
	v_cvt_pk_bf16_f32 v18, v18, s0
	ds_write_b16 v159, v18 offset:5680
	v_mul_f32_e32 v18, v0, v25
	v_mul_f32_e32 v14, v18, v14
	v_cvt_pk_bf16_f32 v14, v14, s0
	ds_write_b16 v159, v14 offset:5952
	v_mul_f32_e32 v14, v0, v26
	v_mul_f32_e32 v14, v14, v15
	v_cvt_pk_bf16_f32 v14, v14, s0
	ds_write_b16 v159, v14 offset:6224
	v_mul_f32_e32 v14, v0, v27
	v_mul_f32_e32 v14, v14, v16
	v_cvt_pk_bf16_f32 v14, v14, s0
	ds_write_b16 v159, v14 offset:6496
	v_mul_f32_e32 v14, v0, v28
	v_mul_f32_e32 v14, v14, v17
	v_cvt_pk_bf16_f32 v14, v14, s0
	ds_write_b16 v159, v14 offset:6768
	v_lshlrev_b32_e32 v14, 16, v2
	v_and_b32_e32 v2, 0xffff0000, v2
	v_mul_f32_e32 v14, v0, v14
	v_mul_f32_e32 v2, v0, v2
	v_mul_f32_e32 v10, v10, v14
	v_mul_f32_e32 v2, v11, v2
	v_lshlrev_b32_e32 v15, 16, v3
	v_cvt_pk_bf16_f32 v10, v10, s0
	v_cvt_pk_bf16_f32 v2, v2, s0
	ds_write_b16 v158, v10 offset:7040
	ds_write_b16 v159, v2 offset:7312
	v_mul_f32_e32 v2, v0, v15
	v_mul_f32_e32 v2, v2, v12
	v_and_b32_e32 v3, 0xffff0000, v3
	v_cvt_pk_bf16_f32 v2, v2, s0
	ds_write_b16 v159, v2 offset:7584
	v_mul_f32_e32 v2, v0, v3
	v_mul_f32_e32 v2, v2, v13
	v_lshlrev_b32_e32 v16, 16, v4
	v_cvt_pk_bf16_f32 v2, v2, s0
	ds_write_b16 v159, v2 offset:7856
	v_mul_f32_e32 v2, v0, v16
	v_mul_f32_e32 v2, v2, v6
	v_and_b32_e32 v4, 0xffff0000, v4
	v_cvt_pk_bf16_f32 v2, v2, s0
	ds_write_b16 v159, v2 offset:8128
	v_mul_f32_e32 v2, v0, v4
	v_mul_f32_e32 v2, v2, v7
	v_lshlrev_b32_e32 v17, 16, v5
	v_and_b32_e32 v5, 0xffff0000, v5
	v_cvt_pk_bf16_f32 v2, v2, s0
	ds_write_b16 v159, v2 offset:8400
	v_mul_f32_e32 v2, v0, v17
	v_mul_f32_e32 v0, v0, v5
	v_mul_f32_e32 v2, v2, v8
	v_mul_f32_e32 v0, v0, v9
	v_cvt_pk_bf16_f32 v2, v2, s0
	v_cvt_pk_bf16_f32 v0, v0, s0
	ds_write_b16 v159, v2 offset:8672
	ds_write_b16 v159, v0 offset:8944
	s_waitcnt lgkmcnt(0)
	s_barrier
	v_cvt_pk_bf16_f32 v18, v90, v91
	v_cvt_pk_bf16_f32 v19, v92, v93
	v_cvt_pk_bf16_f32 v20, v94, v95
	v_cvt_pk_bf16_f32 v21, v96, v97
	v_cvt_pk_bf16_f32 v34, v98, v99
	v_cvt_pk_bf16_f32 v35, v100, v101
	v_cvt_pk_bf16_f32 v36, v162, v163
	v_cvt_pk_bf16_f32 v37, v164, v165
	v_cvt_pk_bf16_f32 v42, v198, v199
	v_cvt_pk_bf16_f32 v43, v200, v201
	v_cvt_pk_bf16_f32 v44, v202, v203
	v_cvt_pk_bf16_f32 v45, v204, v205
	v_cvt_pk_bf16_f32 v50, v206, v207
	v_cvt_pk_bf16_f32 v51, v208, v209
	v_cvt_pk_bf16_f32 v52, v210, v211
	v_cvt_pk_bf16_f32 v53, v212, v213
	global_load_dwordx4 v[90:93], v[144:145], off offset:0
	global_load_dwordx4 v[94:97], v[144:145], off offset:16
	global_load_dwordx4 v[98:101], v[144:145], off offset:64
	global_load_dwordx4 v[162:165], v[144:145], off offset:80
	global_load_dwordx4 v[198:201], v[144:145], off offset:128
	global_load_dwordx4 v[202:205], v[144:145], off offset:144
	global_load_dwordx4 v[206:209], v[144:145], off offset:192
	global_load_dwordx4 v[210:213], v[144:145], off offset:208
	v_lshl_add_u64 v[144:145], v[144:145], 0, s[4:5]
	ds_read_b128 v[26:29], v157 offset:512
	ds_read_b128 v[30:33], v157 offset:544
	ds_read_b128 v[174:177], v157 offset:576
	ds_read_b128 v[214:217], v157 offset:608
	ds_read_b128 v[22:25], v157 offset:9216
	ds_read_b128 v[38:41], v157 offset:9248
	ds_read_b128 v[46:49], v157 offset:9280
	ds_read_b128 v[54:57], v157 offset:9312
	s_waitcnt lgkmcnt(7)
	v_mfma_f32_32x32x16_bf16 v[2:17], v[18:21], v[26:29], 0
	s_waitcnt lgkmcnt(6)
	v_mfma_f32_32x32x16_bf16 v[2:17], v[34:37], v[30:33], v[2:17]
	ds_read_b128 v[26:29], v157 offset:640
	ds_read_b128 v[30:33], v157 offset:672
	s_waitcnt lgkmcnt(7)
	v_mfma_f32_32x32x16_bf16 v[2:17], v[42:45], v[174:177], v[2:17]
	s_waitcnt lgkmcnt(6)
	v_mfma_f32_32x32x16_bf16 v[2:17], v[50:53], v[214:217], v[2:17]
	ds_read_b128 v[174:177], v157 offset:704
	ds_read_b128 v[214:217], v157 offset:736
	ds_read_b128 v[62:65], v157 offset:9344
	ds_read_b128 v[70:73], v157 offset:9376
	ds_read_b128 v[78:81], v157 offset:9408
	ds_read_b128 v[86:89], v157 offset:9440
	s_waitcnt vmcnt(0)
	v_cvt_pk_bf16_f32 v58, v90, v91
	v_cvt_pk_bf16_f32 v59, v92, v93
	v_cvt_pk_bf16_f32 v60, v94, v95
	v_cvt_pk_bf16_f32 v61, v96, v97
	v_cvt_pk_bf16_f32 v66, v98, v99
	v_cvt_pk_bf16_f32 v67, v100, v101
	v_cvt_pk_bf16_f32 v68, v162, v163
	v_cvt_pk_bf16_f32 v69, v164, v165
	v_cvt_pk_bf16_f32 v74, v198, v199
	v_cvt_pk_bf16_f32 v75, v200, v201
	v_cvt_pk_bf16_f32 v76, v202, v203
	v_cvt_pk_bf16_f32 v77, v204, v205
	v_cvt_pk_bf16_f32 v82, v206, v207
	v_cvt_pk_bf16_f32 v83, v208, v209
	v_cvt_pk_bf16_f32 v84, v210, v211
	v_cvt_pk_bf16_f32 v85, v212, v213
	s_waitcnt lgkmcnt(7)
	v_mfma_f32_32x32x16_bf16 v[2:17], v[58:61], v[26:29], v[2:17]
	s_waitcnt lgkmcnt(6)
	v_mfma_f32_32x32x16_bf16 v[2:17], v[66:69], v[30:33], v[2:17]
	s_waitcnt lgkmcnt(5)
	v_mfma_f32_32x32x16_bf16 v[2:17], v[74:77], v[174:177], v[2:17]
	s_waitcnt lgkmcnt(4)
	v_mfma_f32_32x32x16_bf16 v[2:17], v[82:85], v[214:217], v[2:17]
	s_waitcnt lgkmcnt(0)
; __device__ __forceinline__ float bf2f(unsigned v) { return __uint_as_float(v << 16); }
; __device__ __forceinline__ bf16_t f2bf(float f) { return (bf16_t)(pkbf(f, 0.f) & 0xffffu); }
; __device__ __forceinline__ void gmlp_unit(const TI ti, CArgs& a, int l, int u, unsigned char* ldsg) {
;     ...
;             const int s = tid & 127, cc = tid >> 7; const float rs = rstd[s]; const bf16_t* p = GV + (R0 + s) * 1024 + g * 128 + cc * 32;
; #pragma unroll
;             for (int q = 0; q < 4; ++q) {
;                 f32x4 x0, x1; unpack8(*(const u32x4*)(p + 8 * q), x0, x1);
;     ...
;         {
;             const bf16_t* GUr = GU; float uu0[16], uu1[16], bb[16];
; #pragma unroll
;             for (int reg = 0; reg < 16; ++reg) {
;                 const int t = tt * 32 + (reg & 3) + 8 * (reg >> 2) + 4 * h; const size_t i0 = (R0 + t) * 1024 + g * 128 + chh * 64 + r;
;                 bb[reg] = bsp[g * 128 + t]; uu0[reg] = bf2f(GUr[i0]); uu1[reg] = bf2f(GUr[i0 + 32]);
;             }
;             asm volatile("" ::: "memory");
; #pragma unroll
;             for (int reg = 0; reg < 16; ++reg) {
;                 const int t = tt * 32 + (reg & 3) + 8 * (reg >> 2) + 4 * h; const size_t i0 = (R0 + t) * 1024 + g * 128 + chh * 64 + r;
;                 GU[i0] = f2bf(uu0[reg] * (acc0[reg] + bb[reg])); GU[i0 + 32] = f2bf(uu1[reg] * (acc1[reg] + bb[reg]));
;             }
;         }
	v_lshl_add_u64 v[26:27], v[146:147], 0, s[42:43]
	global_load_dwordx4 v[222:225], v[26:27], off offset:16
	global_load_dwordx4 v[226:229], v[26:27], off
	global_load_dwordx4 v[230:233], v[26:27], off offset:-16
	global_load_dwordx4 v[234:237], v[26:27], off offset:-32
	v_lshl_add_u64 v[28:29], v[128:129], 0, s[42:43]
	v_add_co_u32_e32 v148, vcc, s82, v28
	v_lshl_add_u64 v[26:27], v[110:111], 0, s[46:47]
	s_nop 0
	v_addc_co_u32_e32 v149, vcc, 0, v29, vcc
	global_load_dwordx4 v[90:93], v[26:27], off
	global_load_dwordx4 v[94:97], v[26:27], off offset:32
	global_load_dwordx4 v[98:101], v[26:27], off offset:64
	global_load_dwordx4 v[162:165], v[26:27], off offset:96
	global_load_ushort v0, v[148:149], off
	global_load_ushort v161, v[148:149], off offset:64
	global_load_ushort v174, v[148:149], off offset:2048
	global_load_ushort v175, v[148:149], off offset:2112
	global_load_ushort v176, v[150:151], off offset:-64
	global_load_ushort v177, v[150:151], off
	global_load_ushort v179, v[150:151], off offset:1984
	global_load_ushort v181, v[150:151], off offset:2048
	v_lshl_add_u64 v[28:29], v[132:133], 0, s[42:43]
	v_add_co_u32_e32 v152, vcc, s82, v28
	v_lshl_add_u64 v[132:133], v[132:133], 0, s[24:25]
	s_nop 0
	v_addc_co_u32_e32 v153, vcc, 0, v29, vcc
	global_load_ushort v197, v[152:153], off
	global_load_ushort v198, v[152:153], off offset:64
	global_load_ushort v199, v[152:153], off offset:2048
	global_load_ushort v200, v[152:153], off offset:2112
	global_load_ushort v201, v[154:155], off offset:-64
	global_load_ushort v202, v[154:155], off
	global_load_ushort v203, v[154:155], off offset:1984
	global_load_ushort v204, v[154:155], off offset:2048
	v_lshl_add_u64 v[28:29], v[136:137], 0, s[42:43]
	v_add_co_u32_e32 v166, vcc, s82, v28
	v_lshl_add_u64 v[136:137], v[136:137], 0, s[24:25]
	s_nop 0
	v_addc_co_u32_e32 v167, vcc, 0, v29, vcc
	global_load_ushort v205, v[166:167], off
	global_load_ushort v206, v[166:167], off offset:64
	global_load_ushort v207, v[166:167], off offset:2048
	global_load_ushort v208, v[166:167], off offset:2112
	v_lshl_add_u64 v[26:27], v[140:141], 0, s[42:43]
	v_add_co_u32_e32 v170, vcc, s82, v26
	v_lshl_add_u64 v[140:141], v[140:141], 0, s[24:25]
	s_nop 0
	v_addc_co_u32_e32 v171, vcc, 0, v27, vcc
	global_load_ushort v213, v[170:171], off
	global_load_ushort v214, v[170:171], off offset:64
	v_lshl_add_u64 v[26:27], v[142:143], 0, s[42:43]
	v_add_co_u32_e32 v182, vcc, s82, v26
	v_lshl_add_u64 v[142:143], v[142:143], 0, s[24:25]
	s_nop 0
	v_addc_co_u32_e32 v183, vcc, 0, v27, vcc
	v_add_co_u32_e32 v184, vcc, s3, v26
	s_nop 1
	v_addc_co_u32_e32 v185, vcc, 0, v27, vcc
	global_load_ushort v209, v[168:169], off offset:-64
	global_load_ushort v210, v[168:169], off
	global_load_ushort v211, v[168:169], off offset:1984
	global_load_ushort v212, v[168:169], off offset:2048
	global_load_ushort v217, v[184:185], off
	global_load_ushort v218, v[184:185], off offset:64
	global_load_ushort v219, v[184:185], off offset:2048
	global_load_ushort v220, v[184:185], off offset:2112
	global_load_ushort v215, v[182:183], off offset:2048
	global_load_ushort v216, v[182:183], off offset:2112
	v_lshl_add_u64 v[128:129], v[128:129], 0, s[24:25]
	s_add_u32 s46, s46, 0x200
	s_addc_u32 s47, s47, 0
	s_cmpk_lg_i32 s46, 0x1000
	s_waitcnt vmcnt(0)
	v_lshlrev_b32_e32 v0, 16, v0
	v_lshlrev_b32_e32 v161, 16, v161
	v_lshlrev_b32_e32 v174, 16, v174
	v_lshlrev_b32_e32 v175, 16, v175
	v_lshlrev_b32_e32 v176, 16, v176
	v_lshlrev_b32_e32 v177, 16, v177
	v_lshlrev_b32_e32 v179, 16, v179
	v_lshlrev_b32_e32 v181, 16, v181
	v_lshlrev_b32_e32 v197, 16, v197
	v_lshlrev_b32_e32 v198, 16, v198
	v_lshlrev_b32_e32 v199, 16, v199
	v_lshlrev_b32_e32 v200, 16, v200
	v_lshlrev_b32_e32 v201, 16, v201
	v_lshlrev_b32_e32 v202, 16, v202
	v_lshlrev_b32_e32 v203, 16, v203
	v_lshlrev_b32_e32 v204, 16, v204
	v_lshlrev_b32_e32 v205, 16, v205
	v_lshlrev_b32_e32 v206, 16, v206
	v_lshlrev_b32_e32 v207, 16, v207
	v_lshlrev_b32_e32 v208, 16, v208
	v_lshlrev_b32_e32 v209, 16, v209
	v_lshlrev_b32_e32 v210, 16, v210
	v_lshlrev_b32_e32 v211, 16, v211
	v_lshlrev_b32_e32 v212, 16, v212
	v_lshlrev_b32_e32 v213, 16, v213
	v_lshlrev_b32_e32 v214, 16, v214
	v_lshlrev_b32_e32 v215, 16, v215
	v_lshlrev_b32_e32 v216, 16, v216
	v_lshlrev_b32_e32 v217, 16, v217
	v_lshlrev_b32_e32 v218, 16, v218
	v_lshlrev_b32_e32 v219, 16, v219
	v_lshlrev_b32_e32 v220, 16, v220
	v_add_f32_e32 v2, v2, v90
	v_mul_f32_e32 v0, v2, v0
	v_cvt_pk_bf16_f32 v0, v0, s0
	global_store_short v[148:149], v0, off
	v_mfma_f32_32x32x16_bf16 v[18:33], v[18:21], v[22:25], 0
	v_mfma_f32_32x32x16_bf16 v[18:33], v[34:37], v[38:41], v[18:33]
	v_mfma_f32_32x32x16_bf16 v[18:33], v[42:45], v[46:49], v[18:33]
	v_mfma_f32_32x32x16_bf16 v[18:33], v[50:53], v[54:57], v[18:33]
	v_mfma_f32_32x32x16_bf16 v[18:33], v[58:61], v[62:65], v[18:33]
	v_mfma_f32_32x32x16_bf16 v[18:33], v[66:69], v[70:73], v[18:33]
	v_mfma_f32_32x32x16_bf16 v[18:33], v[74:77], v[78:81], v[18:33]
	s_waitcnt lgkmcnt(0)
; __device__ __forceinline__ bf16_t f2bf(float f) { return (bf16_t)(pkbf(f, 0.f) & 0xffffu); }
; __device__ __forceinline__ void gmlp_unit(const TI ti, CArgs& a, int l, int u, unsigned char* ldsg) {
;     ...
; #pragma unroll
;             for (int reg = 0; reg < 16; ++reg) {
;                 const int t = tt * 32 + (reg & 3) + 8 * (reg >> 2) + 4 * h; const size_t i0 = (R0 + t) * 1024 + g * 128 + chh * 64 + r;
;                 GU[i0] = f2bf(uu0[reg] * (acc0[reg] + bb[reg])); GU[i0 + 32] = f2bf(uu1[reg] * (acc1[reg] + bb[reg]));
;             }
;         }
;         __syncthreads();
;     }
	v_mfma_f32_32x32x16_bf16 v[18:33], v[82:85], v[86:89], v[18:33]
	s_nop 11
	v_add_f32_e32 v0, v90, v18
	v_mul_f32_e32 v0, v0, v161
	v_cvt_pk_bf16_f32 v0, v0, s0
	global_store_short v[148:149], v0, off offset:64
	v_add_f32_e32 v0, v3, v91
	v_mul_f32_e32 v0, v0, v174
	v_cvt_pk_bf16_f32 v0, v0, s0
	global_store_short v[148:149], v0, off offset:2048
	v_add_f32_e32 v0, v91, v19
	v_mul_f32_e32 v0, v0, v175
	v_cvt_pk_bf16_f32 v0, v0, s0
	global_store_short v[148:149], v0, off offset:2112
	v_add_f32_e32 v0, v4, v92
	v_mul_f32_e32 v0, v0, v176
	v_cvt_pk_bf16_f32 v0, v0, s0
	global_store_short v[150:151], v0, off offset:-64
	v_add_f32_e32 v0, v92, v20
	v_mul_f32_e32 v0, v0, v177
	v_cvt_pk_bf16_f32 v0, v0, s0
	global_store_short v[150:151], v0, off
	v_add_f32_e32 v0, v5, v93
	v_mul_f32_e32 v0, v0, v179
	v_cvt_pk_bf16_f32 v0, v0, s0
	global_store_short v[150:151], v0, off offset:1984
	v_add_f32_e32 v0, v93, v21
	v_mul_f32_e32 v0, v0, v181
	v_cvt_pk_bf16_f32 v0, v0, s0
	global_store_short v[150:151], v0, off offset:2048
	v_add_f32_e32 v0, v6, v94
	v_mul_f32_e32 v0, v0, v197
	v_cvt_pk_bf16_f32 v0, v0, s0
	global_store_short v[152:153], v0, off
	v_add_f32_e32 v0, v94, v22
	v_mul_f32_e32 v0, v0, v198
	v_cvt_pk_bf16_f32 v0, v0, s0
	global_store_short v[152:153], v0, off offset:64
	v_add_f32_e32 v0, v7, v95
	v_mul_f32_e32 v0, v0, v199
	v_cvt_pk_bf16_f32 v0, v0, s0
	global_store_short v[152:153], v0, off offset:2048
	v_add_f32_e32 v0, v95, v23
	v_mul_f32_e32 v0, v0, v200
	v_cvt_pk_bf16_f32 v0, v0, s0
	global_store_short v[152:153], v0, off offset:2112
	v_add_f32_e32 v0, v8, v96
	v_mul_f32_e32 v0, v0, v201
	v_cvt_pk_bf16_f32 v0, v0, s0
	global_store_short v[154:155], v0, off offset:-64
	v_add_f32_e32 v0, v96, v24
	v_mul_f32_e32 v0, v0, v202
	v_cvt_pk_bf16_f32 v0, v0, s0
	global_store_short v[154:155], v0, off
	v_add_f32_e32 v0, v9, v97
	v_mul_f32_e32 v0, v0, v203
	v_cvt_pk_bf16_f32 v0, v0, s0
	global_store_short v[154:155], v0, off offset:1984
	v_add_f32_e32 v0, v97, v25
	v_mul_f32_e32 v0, v0, v204
	v_cvt_pk_bf16_f32 v0, v0, s0
	global_store_short v[154:155], v0, off offset:2048
	v_add_f32_e32 v0, v10, v98
	v_mul_f32_e32 v0, v0, v205
	v_cvt_pk_bf16_f32 v0, v0, s0
	global_store_short v[166:167], v0, off
	v_add_f32_e32 v0, v98, v26
	v_mul_f32_e32 v0, v0, v206
	v_cvt_pk_bf16_f32 v0, v0, s0
	global_store_short v[166:167], v0, off offset:64
	v_add_f32_e32 v0, v11, v99
	v_mul_f32_e32 v0, v0, v207
	v_cvt_pk_bf16_f32 v0, v0, s0
	global_store_short v[166:167], v0, off offset:2048
	v_add_f32_e32 v0, v99, v27
	v_mul_f32_e32 v0, v0, v208
	v_cvt_pk_bf16_f32 v0, v0, s0
	global_store_short v[166:167], v0, off offset:2112
	v_add_f32_e32 v0, v12, v100
	v_mul_f32_e32 v0, v0, v209
	v_cvt_pk_bf16_f32 v0, v0, s0
	global_store_short v[168:169], v0, off offset:-64
	v_add_f32_e32 v0, v100, v28
	v_mul_f32_e32 v0, v0, v210
	v_cvt_pk_bf16_f32 v0, v0, s0
	global_store_short v[168:169], v0, off
	v_add_f32_e32 v0, v13, v101
	v_mul_f32_e32 v0, v0, v211
	v_cvt_pk_bf16_f32 v0, v0, s0
	global_store_short v[168:169], v0, off offset:1984
	v_add_f32_e32 v0, v101, v29
	v_mul_f32_e32 v0, v0, v212
	v_cvt_pk_bf16_f32 v0, v0, s0
	global_store_short v[168:169], v0, off offset:2048
	v_add_f32_e32 v0, v14, v162
	v_mul_f32_e32 v0, v0, v213
	v_cvt_pk_bf16_f32 v0, v0, s0
	global_store_short v[170:171], v0, off
	v_add_f32_e32 v0, v162, v30
	v_mul_f32_e32 v0, v0, v214
	v_cvt_pk_bf16_f32 v0, v0, s0
	global_store_short v[170:171], v0, off offset:64
	v_add_f32_e32 v0, v15, v163
	v_mul_f32_e32 v0, v0, v215
	v_cvt_pk_bf16_f32 v0, v0, s0
	global_store_short v[182:183], v0, off offset:2048
	v_add_f32_e32 v0, v163, v31
	v_mul_f32_e32 v0, v0, v216
	v_cvt_pk_bf16_f32 v0, v0, s0
	global_store_short v[182:183], v0, off offset:2112
	v_add_f32_e32 v0, v16, v164
	v_mul_f32_e32 v0, v0, v217
	v_cvt_pk_bf16_f32 v0, v0, s0
	global_store_short v[184:185], v0, off
	v_add_f32_e32 v0, v164, v32
	v_mul_f32_e32 v0, v0, v218
	v_cvt_pk_bf16_f32 v0, v0, s0
	global_store_short v[184:185], v0, off offset:64
	v_add_f32_e32 v0, v17, v165
	v_mul_f32_e32 v0, v0, v219
	v_cvt_pk_bf16_f32 v0, v0, s0
	global_store_short v[184:185], v0, off offset:2048
	v_add_f32_e32 v0, v165, v33
	v_mul_f32_e32 v0, v0, v220
	v_cvt_pk_bf16_f32 v0, v0, s0
	global_store_short v[184:185], v0, off offset:2112
	s_barrier
	s_cbranch_scc1 .LBB0_447
	s_add_i32 s1, s1, s0
	v_lshl_add_u64 v[104:105], v[104:105], 0, s[44:45]
	v_lshl_add_u64 v[106:107], v[106:107], 0, s[44:45]
	v_lshl_add_u64 v[112:113], v[112:113], 0, s[44:45]
	v_lshl_add_u64 v[114:115], v[114:115], 0, s[44:45]
	v_lshl_add_u64 v[116:117], v[116:117], 0, s[44:45]
	v_lshl_add_u64 v[118:119], v[118:119], 0, s[44:45]
	v_lshl_add_u64 v[120:121], v[120:121], 0, s[44:45]
	v_lshl_add_u64 v[122:123], v[122:123], 0, s[44:45]
	v_lshl_add_u64 v[124:125], v[124:125], 0, s[44:45]
	s_cmp_ge_i32 s1, s10
	v_lshl_add_u64 v[126:127], v[126:127], 0, s[44:45]
	s_cbranch_scc0 .LBB0_436
